# hg_out scores MFMAs: LDS reads 2 ahead; FFN-in epilogue row-statistic loads issued before the alignment barrier
# speedup vs baseline: 1.0270x; 1.0062x over previous
.LBB0_444:
	s_or_b64 exec, exec, s[14:15]
	v_mul_u32_u24_e32 v147, 0x44, v173
	v_lshl_add_u32 v147, v147, 2, v113
	ds_read_b32 v175, v147
	v_mad_u32_u24 v173, v173, s20, v102
	v_lshl_add_u32 v173, v173, 2, v135
	ds_read_b32 v177, v173
	s_ashr_i32 s14, s29, 2
	s_waitcnt lgkmcnt(1)
	v_lshlrev_b32_e32 v174, 16, v175
	v_and_b32_e32 v175, 0xffff0000, v175
	v_pk_add_f32 v[198:199], v[174:175], 1.0 op_sel_hi:[1,0] neg_lo:[1,0] neg_hi:[1,0]
	s_waitcnt lgkmcnt(0)
	v_lshlrev_b32_e32 v176, 16, v177
	v_pk_mul_f32 v[84:85], v[84:85], v[198:199]
	v_and_b32_e32 v177, 0xffff0000, v177
	v_max_f32_e32 v197, 0xda24260, v84
	v_rcp_f32_e32 v198, v197
	v_max_f32_e32 v197, 0xda24260, v85
	v_rcp_f32_e32 v199, v197
	s_ashr_i32 s15, s14, 31
	s_lshl_b64 vcc, s[14:15], 6
	s_and_b32 s14, s29, 3
	v_pk_mul_f32 v[174:175], v[198:199], v[174:175]
	s_lshl_b32 s15, s14, 23
	v_cvt_pk_bf16_f32 v174, v174, v175
	ds_write_b32 v147, v174
	v_pk_mul_f32 v[174:175], v[84:85], v[176:177]
	s_add_u32 s16, s86, s15
	v_cvt_pk_bf16_f32 v147, v174, v175
	ds_write_b32 v173, v147
	global_load_dwordx4 v[50:53], v[34:35], off
	v_mul_u32_u24_e32 v147, 0x44, v172
	v_lshl_add_u32 v147, v147, 2, v113
	ds_read_b32 v173, v147
	v_mad_u32_u24 v174, v172, s20, v102
	v_lshl_add_u32 v197, v174, 2, v135
	ds_read_b32 v175, v197
	s_addc_u32 s17, s87, 0
	s_waitcnt lgkmcnt(1)
	v_lshlrev_b32_e32 v172, 16, v173
	v_and_b32_e32 v173, 0xffff0000, v173
	v_pk_add_f32 v[176:177], v[172:173], 1.0 op_sel_hi:[1,0] neg_lo:[1,0] neg_hi:[1,0]
	s_waitcnt lgkmcnt(0)
	v_lshlrev_b32_e32 v174, 16, v175
	v_pk_mul_f32 v[84:85], v[84:85], v[176:177]
	v_and_b32_e32 v175, 0xffff0000, v175
	v_max_f32_e32 v176, 0xda24260, v84
	v_max_f32_e32 v177, 0xda24260, v85
	v_rcp_f32_e32 v176, v176
	v_rcp_f32_e32 v177, v177
	s_brev_b32 s15, 8
	s_lshl_b32 s80, s14, 9
	v_pk_mul_f32 v[172:173], v[176:177], v[172:173]
	s_mov_b32 s29, s28
	v_cvt_pk_bf16_f32 v172, v172, v173
	ds_write_b32 v147, v172
	v_pk_mul_f32 v[172:173], v[84:85], v[174:175]
	s_nop 0
	v_cvt_pk_bf16_f32 v147, v172, v173
	ds_write_b32 v197, v147
	global_load_dwordx4 v[46:49], v[82:83], off offset:-192
	v_mul_u32_u24_e32 v147, 0x44, v171
	v_lshl_add_u32 v147, v147, 2, v113
	ds_read_b32 v173, v147
	v_mad_u32_u24 v171, v171, s20, v102
	v_lshl_add_u32 v171, v171, 2, v135
	ds_read_b32 v175, v171
	s_waitcnt lgkmcnt(1)
	v_lshlrev_b32_e32 v172, 16, v173
	v_and_b32_e32 v173, 0xffff0000, v173
	v_pk_add_f32 v[176:177], v[172:173], 1.0 op_sel_hi:[1,0] neg_lo:[1,0] neg_hi:[1,0]
	s_waitcnt lgkmcnt(0)
	v_lshlrev_b32_e32 v174, 16, v175
	v_pk_mul_f32 v[84:85], v[84:85], v[176:177]
	v_and_b32_e32 v175, 0xffff0000, v175
	v_max_f32_e32 v176, 0xda24260, v84
	v_max_f32_e32 v177, 0xda24260, v85
	v_rcp_f32_e32 v176, v176
	v_rcp_f32_e32 v177, v177
	s_nop 0
	v_pk_mul_f32 v[172:173], v[176:177], v[172:173]
	s_nop 0
	v_cvt_pk_bf16_f32 v172, v172, v173
	ds_write_b32 v147, v172
	v_pk_mul_f32 v[172:173], v[84:85], v[174:175]
	s_nop 0
	v_cvt_pk_bf16_f32 v147, v172, v173
	ds_write_b32 v171, v147
	global_load_dwordx4 v[42:45], v[82:83], off offset:-128
	v_mul_u32_u24_e32 v147, 0x44, v170
	v_lshl_add_u32 v147, v147, 2, v113
	ds_read_b32 v171, v147
	v_mad_u32_u24 v172, v170, s20, v102
	v_lshl_add_u32 v176, v172, 2, v135
	ds_read_b32 v173, v176
	s_waitcnt lgkmcnt(1)
	v_lshlrev_b32_e32 v170, 16, v171
	v_and_b32_e32 v171, 0xffff0000, v171
	v_pk_add_f32 v[174:175], v[170:171], 1.0 op_sel_hi:[1,0] neg_lo:[1,0] neg_hi:[1,0]
	s_waitcnt lgkmcnt(0)
	v_lshlrev_b32_e32 v172, 16, v173
	v_pk_mul_f32 v[84:85], v[84:85], v[174:175]
	v_and_b32_e32 v173, 0xffff0000, v173
	v_max_f32_e32 v174, 0xda24260, v84
	v_max_f32_e32 v175, 0xda24260, v85
	v_rcp_f32_e32 v174, v174
	v_rcp_f32_e32 v175, v175
	s_nop 0
	v_pk_mul_f32 v[170:171], v[174:175], v[170:171]
	s_nop 0
	v_cvt_pk_bf16_f32 v170, v170, v171
	ds_write_b32 v147, v170
	v_pk_mul_f32 v[170:171], v[84:85], v[172:173]
	s_nop 0
	v_cvt_pk_bf16_f32 v147, v170, v171
	ds_write_b32 v176, v147
	global_load_dwordx4 v[38:41], v[82:83], off offset:-64
	v_mul_u32_u24_e32 v147, 0x44, v169
	v_lshl_add_u32 v147, v147, 2, v113
	ds_read_b32 v171, v147
	v_mad_u32_u24 v169, v169, s20, v102
	v_lshl_add_u32 v169, v169, 2, v135
	ds_read_b32 v173, v169
	v_add_u32_e32 v176, v137, v73
	s_waitcnt lgkmcnt(1)
	v_lshlrev_b32_e32 v170, 16, v171
	v_and_b32_e32 v171, 0xffff0000, v171
	v_pk_add_f32 v[174:175], v[170:171], 1.0 op_sel_hi:[1,0] neg_lo:[1,0] neg_hi:[1,0]
	s_waitcnt lgkmcnt(0)
	v_lshlrev_b32_e32 v172, 16, v173
	v_pk_mul_f32 v[84:85], v[84:85], v[174:175]
	v_and_b32_e32 v173, 0xffff0000, v173
	v_max_f32_e32 v174, 0xda24260, v84
	v_max_f32_e32 v175, 0xda24260, v85
	v_rcp_f32_e32 v174, v174
	v_rcp_f32_e32 v175, v175
	s_nop 0
	v_pk_mul_f32 v[170:171], v[174:175], v[170:171]
	s_nop 0
	v_cvt_pk_bf16_f32 v170, v170, v171
	ds_write_b32 v147, v170
	v_pk_mul_f32 v[170:171], v[84:85], v[172:173]
	s_nop 0
	v_cvt_pk_bf16_f32 v147, v170, v171
	ds_write_b32 v169, v147
	global_load_dwordx4 v[34:37], v[82:83], off
	v_lshl_add_u64 v[82:83], v[82:83], 0, s[10:11]
	v_mul_u32_u24_e32 v147, 0x44, v168
	v_lshl_add_u32 v147, v147, 2, v113
	ds_read_b32 v169, v147
	v_mad_u32_u24 v170, v168, s20, v102
	v_lshl_add_u32 v174, v170, 2, v135
	ds_read_b32 v171, v174
	s_waitcnt lgkmcnt(1)
	v_lshlrev_b32_e32 v168, 16, v169
	v_and_b32_e32 v169, 0xffff0000, v169
	v_pk_add_f32 v[172:173], v[168:169], 1.0 op_sel_hi:[1,0] neg_lo:[1,0] neg_hi:[1,0]
	s_waitcnt lgkmcnt(0)
	v_lshlrev_b32_e32 v170, 16, v171
	v_pk_mul_f32 v[84:85], v[84:85], v[172:173]
	v_and_b32_e32 v171, 0xffff0000, v171
	v_max_f32_e32 v172, 0xda24260, v84
	v_max_f32_e32 v173, 0xda24260, v85
	v_rcp_f32_e32 v172, v172
	v_rcp_f32_e32 v173, v173
	s_nop 0
	v_pk_mul_f32 v[168:169], v[172:173], v[168:169]
	s_nop 0
	v_cvt_pk_bf16_f32 v168, v168, v169
	ds_write_b32 v147, v168
	v_pk_mul_f32 v[168:169], v[84:85], v[170:171]
	s_nop 0
	v_cvt_pk_bf16_f32 v147, v168, v169
	ds_write_b32 v174, v147
	global_load_dwordx4 v[2:5], v236, s[100:101]
	v_mul_u32_u24_e32 v147, 0x44, v95
	v_lshl_add_u32 v147, v147, 2, v113
	ds_read_b32 v169, v147
	v_mad_u32_u24 v95, v95, s20, v102
	v_lshl_add_u32 v95, v95, 2, v135
	ds_read_b32 v171, v95
	s_waitcnt lgkmcnt(1)
	v_lshlrev_b32_e32 v168, 16, v169
	v_and_b32_e32 v169, 0xffff0000, v169
	v_pk_add_f32 v[172:173], v[168:169], 1.0 op_sel_hi:[1,0] neg_lo:[1,0] neg_hi:[1,0]
	s_waitcnt lgkmcnt(0)
	v_lshlrev_b32_e32 v170, 16, v171
	v_pk_mul_f32 v[84:85], v[84:85], v[172:173]
	v_and_b32_e32 v171, 0xffff0000, v171
	v_max_f32_e32 v172, 0xda24260, v84
	v_max_f32_e32 v173, 0xda24260, v85
	v_rcp_f32_e32 v172, v172
	v_rcp_f32_e32 v173, v173
	s_nop 0
	v_pk_mul_f32 v[168:169], v[172:173], v[168:169]
	s_nop 0
	v_cvt_pk_bf16_f32 v168, v168, v169
	ds_write_b32 v147, v168
	v_pk_mul_f32 v[168:169], v[84:85], v[170:171]
	s_nop 0
	v_cvt_pk_bf16_f32 v147, v168, v169
	ds_write_b32 v95, v147
	v_mul_u32_u24_e32 v95, 0x44, v94
	v_lshl_add_u32 v172, v95, 2, v113
	ds_read_b32 v95, v172
	v_mad_u32_u24 v147, v94, s20, v102
	v_lshl_add_u32 v147, v147, 2, v135
	ds_read_b32 v169, v147
	s_waitcnt lgkmcnt(1)
	v_lshlrev_b32_e32 v94, 16, v95
	v_and_b32_e32 v95, 0xffff0000, v95
	v_pk_add_f32 v[170:171], v[94:95], 1.0 op_sel_hi:[1,0] neg_lo:[1,0] neg_hi:[1,0]
	s_waitcnt lgkmcnt(0)
	v_lshlrev_b32_e32 v168, 16, v169
	v_pk_mul_f32 v[84:85], v[84:85], v[170:171]
	v_and_b32_e32 v169, 0xffff0000, v169
	v_max_f32_e32 v170, 0xda24260, v84
	v_max_f32_e32 v171, 0xda24260, v85
	v_rcp_f32_e32 v170, v170
	v_rcp_f32_e32 v171, v171
	s_nop 0
	v_pk_mul_f32 v[94:95], v[170:171], v[94:95]
	s_nop 0
	v_cvt_pk_bf16_f32 v94, v94, v95
	ds_write_b32 v172, v94
	v_pk_mul_f32 v[94:95], v[84:85], v[168:169]
	s_nop 0
	v_cvt_pk_bf16_f32 v94, v94, v95
	ds_write_b32 v147, v94
	global_load_dwordx4 v[6:9], v237, s[100:101]
	v_mul_u32_u24_e32 v94, 0x44, v93
	v_lshl_add_u32 v147, v94, 2, v113
	ds_read_b32 v95, v147
	v_mad_u32_u24 v93, v93, s20, v102
	v_lshl_add_u32 v93, v93, 2, v135
	ds_read_b32 v169, v93
	s_waitcnt lgkmcnt(1)
	v_lshlrev_b32_e32 v94, 16, v95
	v_and_b32_e32 v95, 0xffff0000, v95
	v_pk_add_f32 v[170:171], v[94:95], 1.0 op_sel_hi:[1,0] neg_lo:[1,0] neg_hi:[1,0]
	s_waitcnt lgkmcnt(0)
	v_lshlrev_b32_e32 v168, 16, v169
	v_pk_mul_f32 v[84:85], v[84:85], v[170:171]
	v_and_b32_e32 v169, 0xffff0000, v169
	v_max_f32_e32 v170, 0xda24260, v84
	v_max_f32_e32 v171, 0xda24260, v85
	v_rcp_f32_e32 v170, v170
	v_rcp_f32_e32 v171, v171
	s_nop 0
	v_pk_mul_f32 v[94:95], v[170:171], v[94:95]
	s_nop 0
	v_cvt_pk_bf16_f32 v94, v94, v95
	ds_write_b32 v147, v94
	v_pk_mul_f32 v[94:95], v[84:85], v[168:169]
	s_nop 0
	v_cvt_pk_bf16_f32 v94, v94, v95
	ds_write_b32 v93, v94
	v_mul_u32_u24_e32 v93, 0x44, v92
	v_lshl_add_u32 v147, v93, 2, v113
	ds_read_b32 v93, v147
	v_mad_u32_u24 v94, v92, s20, v102
	v_lshl_add_u32 v170, v94, 2, v135
	ds_read_b32 v95, v170
	s_waitcnt lgkmcnt(1)
	v_lshlrev_b32_e32 v92, 16, v93
	v_and_b32_e32 v93, 0xffff0000, v93
	v_pk_add_f32 v[168:169], v[92:93], 1.0 op_sel_hi:[1,0] neg_lo:[1,0] neg_hi:[1,0]
	s_waitcnt lgkmcnt(0)
	v_lshlrev_b32_e32 v94, 16, v95
	v_pk_mul_f32 v[84:85], v[84:85], v[168:169]
	v_and_b32_e32 v95, 0xffff0000, v95
	v_max_f32_e32 v168, 0xda24260, v84
	v_max_f32_e32 v169, 0xda24260, v85
	v_rcp_f32_e32 v168, v168
	v_rcp_f32_e32 v169, v169
	s_nop 0
	v_pk_mul_f32 v[92:93], v[168:169], v[92:93]
	s_nop 0
	v_cvt_pk_bf16_f32 v92, v92, v93
	ds_write_b32 v147, v92
	v_pk_mul_f32 v[92:93], v[84:85], v[94:95]
	s_nop 0
	v_cvt_pk_bf16_f32 v92, v92, v93
	ds_write_b32 v170, v92
	global_load_dwordx4 v[18:21], v238, s[100:101]
	v_mul_u32_u24_e32 v92, 0x44, v91
	v_lshl_add_u32 v147, v92, 2, v113
	ds_read_b32 v93, v147
	v_mad_u32_u24 v91, v91, s20, v102
	v_lshl_add_u32 v91, v91, 2, v135
	ds_read_b32 v95, v91
	s_waitcnt lgkmcnt(1)
	v_lshlrev_b32_e32 v92, 16, v93
	v_and_b32_e32 v93, 0xffff0000, v93
	v_pk_add_f32 v[168:169], v[92:93], 1.0 op_sel_hi:[1,0] neg_lo:[1,0] neg_hi:[1,0]
	s_waitcnt lgkmcnt(0)
	v_lshlrev_b32_e32 v94, 16, v95
	v_pk_mul_f32 v[84:85], v[84:85], v[168:169]
	v_and_b32_e32 v95, 0xffff0000, v95
	v_max_f32_e32 v168, 0xda24260, v84
	v_max_f32_e32 v169, 0xda24260, v85
	v_rcp_f32_e32 v168, v168
	v_rcp_f32_e32 v169, v169
	s_nop 0
	v_pk_mul_f32 v[92:93], v[168:169], v[92:93]
	s_nop 0
	v_cvt_pk_bf16_f32 v92, v92, v93
	ds_write_b32 v147, v92
	v_pk_mul_f32 v[92:93], v[84:85], v[94:95]
	s_nop 0
	v_cvt_pk_bf16_f32 v92, v92, v93
	ds_write_b32 v91, v92
	v_mul_u32_u24_e32 v91, 0x44, v90
	v_lshl_add_u32 v147, v91, 2, v113
	ds_read_b32 v91, v147
	v_mad_u32_u24 v92, v90, s20, v102
	v_lshl_add_u32 v168, v92, 2, v135
	ds_read_b32 v93, v168
	s_waitcnt lgkmcnt(1)
	v_lshlrev_b32_e32 v90, 16, v91
	v_and_b32_e32 v91, 0xffff0000, v91
	v_pk_add_f32 v[94:95], v[90:91], 1.0 op_sel_hi:[1,0] neg_lo:[1,0] neg_hi:[1,0]
	s_waitcnt lgkmcnt(0)
	v_lshlrev_b32_e32 v92, 16, v93
	v_pk_mul_f32 v[84:85], v[84:85], v[94:95]
	v_and_b32_e32 v93, 0xffff0000, v93
	v_max_f32_e32 v94, 0xda24260, v84
	v_max_f32_e32 v95, 0xda24260, v85
	v_rcp_f32_e32 v94, v94
	v_rcp_f32_e32 v95, v95
	s_nop 0
	v_pk_mul_f32 v[90:91], v[94:95], v[90:91]
	s_nop 0
	v_cvt_pk_bf16_f32 v90, v90, v91
	ds_write_b32 v147, v90
	v_pk_mul_f32 v[90:91], v[84:85], v[92:93]
	s_nop 0
	v_cvt_pk_bf16_f32 v90, v90, v91
	ds_write_b32 v168, v90
	global_load_dwordx4 v[22:25], v239, s[100:101]
	v_mul_u32_u24_e32 v90, 0x44, v89
	v_lshl_add_u32 v147, v90, 2, v113
	ds_read_b32 v91, v147
	v_mad_u32_u24 v89, v89, s20, v102
	v_lshl_add_u32 v89, v89, 2, v135
	ds_read_b32 v93, v89
	s_waitcnt lgkmcnt(1)
	v_lshlrev_b32_e32 v90, 16, v91
	v_and_b32_e32 v91, 0xffff0000, v91
	v_pk_add_f32 v[94:95], v[90:91], 1.0 op_sel_hi:[1,0] neg_lo:[1,0] neg_hi:[1,0]
	s_waitcnt lgkmcnt(0)
	v_lshlrev_b32_e32 v92, 16, v93
	v_pk_mul_f32 v[84:85], v[84:85], v[94:95]
	v_and_b32_e32 v93, 0xffff0000, v93
	v_max_f32_e32 v94, 0xda24260, v84
	v_max_f32_e32 v95, 0xda24260, v85
	v_rcp_f32_e32 v94, v94
	v_rcp_f32_e32 v95, v95
	s_nop 0
	v_pk_mul_f32 v[90:91], v[94:95], v[90:91]
	s_nop 0
	v_cvt_pk_bf16_f32 v90, v90, v91
	ds_write_b32 v147, v90
	v_pk_mul_f32 v[90:91], v[84:85], v[92:93]
	v_add_u32_e32 v147, v137, v71
	v_cvt_pk_bf16_f32 v90, v90, v91
	ds_write_b32 v89, v90
	v_mul_u32_u24_e32 v89, 0x44, v88
	v_lshl_add_u32 v94, v89, 2, v113
	ds_read_b32 v89, v94
	v_mad_u32_u24 v90, v88, s20, v102
	v_lshl_add_u32 v95, v90, 2, v135
	ds_read_b32 v91, v95
	s_waitcnt lgkmcnt(1)
	v_lshlrev_b32_e32 v88, 16, v89
	v_and_b32_e32 v89, 0xffff0000, v89
	v_pk_add_f32 v[92:93], v[88:89], 1.0 op_sel_hi:[1,0] neg_lo:[1,0] neg_hi:[1,0]
	s_waitcnt lgkmcnt(0)
	v_lshlrev_b32_e32 v90, 16, v91
	v_pk_mul_f32 v[84:85], v[84:85], v[92:93]
	v_and_b32_e32 v91, 0xffff0000, v91
	v_max_f32_e32 v92, 0xda24260, v84
	v_max_f32_e32 v93, 0xda24260, v85
	v_rcp_f32_e32 v92, v92
	v_rcp_f32_e32 v93, v93
	s_nop 0
	v_pk_mul_f32 v[88:89], v[92:93], v[88:89]
	s_nop 0
	v_cvt_pk_bf16_f32 v88, v88, v89
	ds_write_b32 v94, v88
	v_pk_mul_f32 v[88:89], v[84:85], v[90:91]
	s_nop 0
	v_cvt_pk_bf16_f32 v88, v88, v89
	ds_write_b32 v95, v88
	global_load_dwordx4 v[10:13], v240, s[100:101]
	v_mul_u32_u24_e32 v88, 0x44, v87
	v_lshl_add_u32 v94, v88, 2, v113
	ds_read_b32 v89, v94
	v_mad_u32_u24 v87, v87, s20, v102
	v_lshl_add_u32 v87, v87, 2, v135
	ds_read_b32 v91, v87
	s_waitcnt lgkmcnt(1)
	v_lshlrev_b32_e32 v88, 16, v89
	v_and_b32_e32 v89, 0xffff0000, v89
	v_pk_add_f32 v[92:93], v[88:89], 1.0 op_sel_hi:[1,0] neg_lo:[1,0] neg_hi:[1,0]
	s_waitcnt lgkmcnt(0)
	v_lshlrev_b32_e32 v90, 16, v91
	v_pk_mul_f32 v[84:85], v[84:85], v[92:93]
	v_and_b32_e32 v91, 0xffff0000, v91
	v_max_f32_e32 v92, 0xda24260, v84
	v_max_f32_e32 v93, 0xda24260, v85
	v_rcp_f32_e32 v92, v92
	v_rcp_f32_e32 v93, v93
	s_nop 0
	v_pk_mul_f32 v[88:89], v[92:93], v[88:89]
	s_nop 0
	v_cvt_pk_bf16_f32 v88, v88, v89
	ds_write_b32 v94, v88
	v_pk_mul_f32 v[88:89], v[84:85], v[90:91]
	s_nop 0
	v_cvt_pk_bf16_f32 v88, v88, v89
	ds_write_b32 v87, v88
	v_mul_u32_u24_e32 v87, 0x44, v86
	v_lshl_add_u32 v92, v87, 2, v113
	ds_read_b32 v87, v92
	v_mad_u32_u24 v88, v86, s20, v102
	v_lshl_add_u32 v93, v88, 2, v135
	ds_read_b32 v89, v93
	s_waitcnt lgkmcnt(1)
	v_lshlrev_b32_e32 v86, 16, v87
	v_and_b32_e32 v87, 0xffff0000, v87
	v_pk_add_f32 v[90:91], v[86:87], 1.0 op_sel_hi:[1,0] neg_lo:[1,0] neg_hi:[1,0]
	s_waitcnt lgkmcnt(0)
	v_lshlrev_b32_e32 v88, 16, v89
	v_pk_mul_f32 v[84:85], v[84:85], v[90:91]
	v_and_b32_e32 v89, 0xffff0000, v89
	v_max_f32_e32 v90, 0xda24260, v84
	v_max_f32_e32 v91, 0xda24260, v85
	v_rcp_f32_e32 v90, v90
	v_rcp_f32_e32 v91, v91
	v_pk_mul_f32 v[84:85], v[84:85], v[88:89]
	v_pk_mul_f32 v[86:87], v[90:91], v[86:87]
	s_nop 0
	v_cvt_pk_bf16_f32 v86, v86, v87
	v_cvt_pk_bf16_f32 v84, v84, v85
	ds_write_b32 v92, v86
	ds_write_b32 v93, v84
	global_load_dwordx4 v[14:17], v241, s[100:101]
	s_waitcnt lgkmcnt(0)
	s_barrier
	ds_read_b128 v[246:249], v136
	ds_read_b128 v[172:175], v147
	ds_read_b128 v[198:201], v147 offset:4352
	ds_read_b128 v[202:205], v147 offset:8704
	s_waitcnt lgkmcnt(2)
	v_mfma_f32_16x16x32_bf16 v[88:91], v[246:249], v[172:175], 0
	ds_read_b128 v[172:175], v176
	s_waitcnt lgkmcnt(2)
	v_mfma_f32_16x16x32_bf16 v[92:95], v[246:249], v[198:201], 0
	ds_read_b128 v[250:253], v136 offset:64
	ds_read_b128 v[198:201], v147 offset:64
	s_waitcnt lgkmcnt(3)
	v_mfma_f32_16x16x32_bf16 v[168:171], v[246:249], v[202:205], 0
	ds_read_b128 v[202:205], v147 offset:4416
	s_waitcnt lgkmcnt(3)
	v_mfma_f32_16x16x32_bf16 v[84:87], v[246:249], v[172:175], 0
	ds_read_b128 v[172:175], v147 offset:8768
	s_waitcnt lgkmcnt(2)
	v_mfma_f32_16x16x32_bf16 v[88:91], v[250:253], v[198:201], v[88:91]
	ds_read_b128 v[198:201], v176 offset:64
	global_load_dwordx4 v[26:29], v242, s[100:101]
	s_waitcnt lgkmcnt(2)
	v_mfma_f32_16x16x32_bf16 v[92:95], v[250:253], v[202:205], v[92:95]
	ds_read_b128 v[246:249], v136 offset:128
	ds_read_b128 v[202:205], v147 offset:128
	s_waitcnt lgkmcnt(3)
	v_mfma_f32_16x16x32_bf16 v[168:171], v[250:253], v[172:175], v[168:171]
	ds_read_b128 v[172:175], v147 offset:4480
	s_waitcnt lgkmcnt(3)
	v_mfma_f32_16x16x32_bf16 v[84:87], v[250:253], v[198:201], v[84:87]
	ds_read_b128 v[198:201], v147 offset:8832
	s_waitcnt lgkmcnt(2)
	v_mfma_f32_16x16x32_bf16 v[88:91], v[246:249], v[202:205], v[88:91]
	ds_read_b128 v[202:205], v176 offset:128
	s_waitcnt lgkmcnt(2)
	v_mfma_f32_16x16x32_bf16 v[92:95], v[246:249], v[172:175], v[92:95]
	ds_read_b128 v[250:253], v136 offset:192
	ds_read_b128 v[172:175], v147 offset:192
	s_waitcnt lgkmcnt(3)
	v_mfma_f32_16x16x32_bf16 v[168:171], v[246:249], v[198:201], v[168:171]
	ds_read_b128 v[198:201], v147 offset:4544
	s_waitcnt lgkmcnt(3)
	v_mfma_f32_16x16x32_bf16 v[84:87], v[246:249], v[202:205], v[84:87]
	ds_read_b128 v[202:205], v147 offset:8896
	s_waitcnt lgkmcnt(2)
	v_mfma_f32_16x16x32_bf16 v[88:91], v[250:253], v[172:175], v[88:91]
	ds_read_b128 v[172:175], v176 offset:192
	s_waitcnt lgkmcnt(2)
	v_mfma_f32_16x16x32_bf16 v[92:95], v[250:253], v[198:201], v[92:95]
	s_waitcnt lgkmcnt(1)
	v_mfma_f32_16x16x32_bf16 v[168:171], v[250:253], v[202:205], v[168:171]
	s_waitcnt lgkmcnt(0)
	v_mfma_f32_16x16x32_bf16 v[84:87], v[250:253], v[172:175], v[84:87]
	s_nop 7
	v_cvt_pk_bf16_f32 v88, v88, s0
	v_cvt_pk_bf16_f32 v89, v89, s0
	v_cvt_pk_bf16_f32 v90, v90, s0
	v_cvt_pk_bf16_f32 v91, v91, s0
	v_cndmask_b32_e64 v88, 0, v88, s[42:43]
	v_cndmask_b32_e64 v89, 0, v89, s[44:45]
	v_cndmask_b32_e64 v90, 0, v90, s[46:47]
	v_cndmask_b32_e64 v91, 0, v91, s[48:49]
	v_perm_b32 v88, v89, v88, s21
	v_perm_b32 v89, v91, v90, s21
	v_add_u32_e32 v90, v138, v75
	global_load_dwordx4 v[30:33], v243, s[100:101]
	ds_write_b64 v90, v[88:89]
	v_cvt_pk_bf16_f32 v88, v92, s0
	v_cvt_pk_bf16_f32 v89, v93, s0
	v_cvt_pk_bf16_f32 v91, v94, s0
	v_cvt_pk_bf16_f32 v92, v95, s0
	v_cndmask_b32_e64 v88, 0, v88, s[50:51]
	v_cndmask_b32_e64 v89, 0, v89, s[52:53]
	v_cndmask_b32_e64 v91, 0, v91, s[54:55]
	v_cndmask_b32_e64 v92, 0, v92, s[56:57]
	v_perm_b32 v88, v89, v88, s21
	v_perm_b32 v89, v92, v91, s21
	ds_write_b64 v90, v[88:89] offset:2304
	v_cvt_pk_bf16_f32 v88, v168, s0
	v_cvt_pk_bf16_f32 v89, v169, s0
	v_cvt_pk_bf16_f32 v91, v170, s0
	v_cvt_pk_bf16_f32 v92, v171, s0
	v_cvt_pk_bf16_f32 v84, v84, s0
	v_cvt_pk_bf16_f32 v85, v85, s0
	v_cvt_pk_bf16_f32 v86, v86, s0
	v_cvt_pk_bf16_f32 v87, v87, s0
	v_cndmask_b32_e64 v88, 0, v88, s[58:59]
	v_cndmask_b32_e64 v89, 0, v89, s[60:61]
	v_cndmask_b32_e64 v91, 0, v91, s[62:63]
	v_cndmask_b32_e64 v92, 0, v92, s[64:65]
	v_cndmask_b32_e64 v84, 0, v84, s[66:67]
	v_cndmask_b32_e64 v85, 0, v85, s[68:69]
	v_cndmask_b32_e64 v86, 0, v86, s[70:71]
	v_cndmask_b32_e64 v87, 0, v87, s[72:73]
	v_perm_b32 v88, v89, v88, s21
	v_perm_b32 v89, v92, v91, s21
	v_perm_b32 v84, v85, v84, s21
	v_perm_b32 v85, v87, v86, s21
	v_add_u32_e32 v86, v138, v96
	ds_write_b64 v90, v[88:89] offset:4608
	ds_write_b64 v86, v[84:85]
	s_waitcnt lgkmcnt(0)
	s_barrier
	ds_read_b64_tr_b16 v[84:85], v164
	ds_read_b64_tr_b16 v[86:87], v164 offset:1088
	ds_read_b128 v[88:91], v139
	ds_read_b128 v[92:95], v140
	s_waitcnt lgkmcnt(1)
	v_mfma_f32_16x16x32_bf16 v[88:91], v[88:91], v[84:87], 0
	v_add_u32_e32 v147, v106, v71
	v_add_u32_e32 v176, v106, v73
	s_waitcnt lgkmcnt(0)
	v_mfma_f32_16x16x32_bf16 v[88:91], v[92:95], v[84:87], v[88:91]
	ds_read_b128 v[92:95], v141
	ds_read_b128 v[168:171], v142
	s_waitcnt lgkmcnt(1)
	v_mfma_f32_16x16x32_bf16 v[92:95], v[92:95], v[84:87], 0
	s_waitcnt lgkmcnt(0)
	v_mfma_f32_16x16x32_bf16 v[92:95], v[168:171], v[84:87], v[92:95]
	ds_read_b128 v[168:171], v143
	ds_read_b128 v[172:175], v144
	s_waitcnt lgkmcnt(1)
	v_mfma_f32_16x16x32_bf16 v[168:171], v[168:171], v[84:87], 0
	s_waitcnt lgkmcnt(0)
	v_mfma_f32_16x16x32_bf16 v[168:171], v[172:175], v[84:87], v[168:171]
	ds_read_b128 v[172:175], v145
	ds_read_b128 v[198:201], v152
	s_waitcnt lgkmcnt(1)
	v_mfma_f32_16x16x32_bf16 v[172:175], v[172:175], v[84:87], 0
	s_waitcnt lgkmcnt(0)
	v_mfma_f32_16x16x32_bf16 v[84:87], v[198:201], v[84:87], v[172:175]
	s_nop 5
	ds_read_b64_tr_b16 v[172:173], v165
	ds_read_b64_tr_b16 v[174:175], v165 offset:1088
	ds_read_b128 v[198:201], v153
	ds_read_b128 v[202:205], v154
	s_waitcnt lgkmcnt(1)
	v_mfma_f32_16x16x32_bf16 v[88:91], v[198:201], v[172:175], v[88:91]
	s_waitcnt lgkmcnt(0)
	v_mfma_f32_16x16x32_bf16 v[88:91], v[202:205], v[172:175], v[88:91]
	ds_read_b128 v[198:201], v155
	ds_read_b128 v[202:205], v156
	s_waitcnt lgkmcnt(1)
	v_mfma_f32_16x16x32_bf16 v[92:95], v[198:201], v[172:175], v[92:95]
	s_waitcnt lgkmcnt(0)
	v_mfma_f32_16x16x32_bf16 v[92:95], v[202:205], v[172:175], v[92:95]
	ds_read_b128 v[198:201], v157
	ds_read_b128 v[202:205], v158
	s_waitcnt lgkmcnt(1)
	v_mfma_f32_16x16x32_bf16 v[168:171], v[198:201], v[172:175], v[168:171]
	s_waitcnt lgkmcnt(0)
	v_mfma_f32_16x16x32_bf16 v[168:171], v[202:205], v[172:175], v[168:171]
	ds_read_b128 v[198:201], v159
	ds_read_b128 v[202:205], v160
	s_waitcnt lgkmcnt(1)
	v_mfma_f32_16x16x32_bf16 v[84:87], v[198:201], v[172:175], v[84:87]
	s_waitcnt lgkmcnt(0)
	v_mfma_f32_16x16x32_bf16 v[84:87], v[202:205], v[172:175], v[84:87]
	ds_read_b128 v[172:175], v147
	ds_read_b128 v[198:201], v147 offset:4352
	ds_read_b128 v[202:205], v147 offset:8704
	ds_read_b128 v[246:249], v176
	s_lshl_b32 s80, s14, 8
	ds_read_b128 v[250:253], v147 offset:64
	s_waitcnt vmcnt(15) lgkmcnt(4)
	v_mfma_f32_16x16x32_bf16 v[88:91], v[172:175], v[62:65], v[88:91]
	ds_read_b128 v[172:175], v147 offset:4416
	s_waitcnt lgkmcnt(4)
	v_mfma_f32_16x16x32_bf16 v[92:95], v[198:201], v[62:65], v[92:95]
	ds_read_b128 v[198:201], v147 offset:8768
	s_waitcnt lgkmcnt(4)
	v_mfma_f32_16x16x32_bf16 v[168:171], v[202:205], v[62:65], v[168:171]
	ds_read_b128 v[202:205], v176 offset:64
	s_waitcnt lgkmcnt(4)
	v_mfma_f32_16x16x32_bf16 v[84:87], v[246:249], v[62:65], v[84:87]
	ds_read_b128 v[246:249], v147 offset:128
	s_waitcnt vmcnt(14) lgkmcnt(4)
	v_mfma_f32_16x16x32_bf16 v[88:91], v[250:253], v[58:61], v[88:91]
	ds_read_b128 v[250:253], v147 offset:4480
	s_waitcnt lgkmcnt(4)
	v_mfma_f32_16x16x32_bf16 v[92:95], v[172:175], v[58:61], v[92:95]
	ds_read_b128 v[172:175], v147 offset:8832
	s_waitcnt lgkmcnt(4)
	v_mfma_f32_16x16x32_bf16 v[168:171], v[198:201], v[58:61], v[168:171]
	ds_read_b128 v[198:201], v176 offset:128
	s_waitcnt lgkmcnt(4)
	v_mfma_f32_16x16x32_bf16 v[84:87], v[202:205], v[58:61], v[84:87]
	ds_read_b128 v[202:205], v147 offset:192
	s_waitcnt vmcnt(13) lgkmcnt(4)
	v_mfma_f32_16x16x32_bf16 v[88:91], v[246:249], v[54:57], v[88:91]
	ds_read_b128 v[246:249], v147 offset:4544
	s_waitcnt lgkmcnt(4)
	v_mfma_f32_16x16x32_bf16 v[92:95], v[250:253], v[54:57], v[92:95]
	ds_read_b128 v[250:253], v147 offset:8896
	s_waitcnt lgkmcnt(4)
	v_mfma_f32_16x16x32_bf16 v[168:171], v[172:175], v[54:57], v[168:171]
	ds_read_b128 v[172:175], v176 offset:192
	s_waitcnt lgkmcnt(4)
	v_mfma_f32_16x16x32_bf16 v[84:87], v[198:201], v[54:57], v[84:87]
	ds_read_b128 v[198:201], v147 offset:17408
	s_waitcnt vmcnt(12) lgkmcnt(4)
	v_mfma_f32_16x16x32_bf16 v[88:91], v[202:205], v[50:53], v[88:91]
	ds_read_b128 v[202:205], v147 offset:21760
	s_waitcnt lgkmcnt(4)
	v_mfma_f32_16x16x32_bf16 v[92:95], v[246:249], v[50:53], v[92:95]
	ds_read_b128 v[246:249], v147 offset:26112
	s_waitcnt lgkmcnt(4)
	v_mfma_f32_16x16x32_bf16 v[168:171], v[250:253], v[50:53], v[168:171]
	ds_read_b128 v[250:253], v176 offset:17408
	s_waitcnt lgkmcnt(4)
	v_mfma_f32_16x16x32_bf16 v[84:87], v[172:175], v[50:53], v[84:87]
	ds_read_b128 v[172:175], v147 offset:17472
	s_waitcnt vmcnt(11) lgkmcnt(4)
	v_mfma_f32_16x16x32_bf16 v[88:91], v[198:201], v[46:49], v[88:91]
	ds_read_b128 v[198:201], v147 offset:21824
	s_waitcnt lgkmcnt(4)
	v_mfma_f32_16x16x32_bf16 v[92:95], v[202:205], v[46:49], v[92:95]
	ds_read_b128 v[202:205], v147 offset:26176
	s_waitcnt lgkmcnt(4)
	v_mfma_f32_16x16x32_bf16 v[168:171], v[246:249], v[46:49], v[168:171]
	ds_read_b128 v[246:249], v176 offset:17472
	s_waitcnt lgkmcnt(4)
	v_mfma_f32_16x16x32_bf16 v[84:87], v[250:253], v[46:49], v[84:87]
	ds_read_b128 v[250:253], v147 offset:17536
	s_waitcnt vmcnt(10) lgkmcnt(4)
	v_mfma_f32_16x16x32_bf16 v[88:91], v[172:175], v[42:45], v[88:91]
	ds_read_b128 v[172:175], v147 offset:21888
	s_waitcnt lgkmcnt(4)
	v_mfma_f32_16x16x32_bf16 v[92:95], v[198:201], v[42:45], v[92:95]
	ds_read_b128 v[198:201], v147 offset:26240
	s_waitcnt lgkmcnt(4)
	v_mfma_f32_16x16x32_bf16 v[168:171], v[202:205], v[42:45], v[168:171]
	ds_read_b128 v[202:205], v176 offset:17536
	s_waitcnt lgkmcnt(4)
	v_mfma_f32_16x16x32_bf16 v[84:87], v[246:249], v[42:45], v[84:87]
	ds_read_b128 v[246:249], v147 offset:17600
	s_waitcnt vmcnt(9) lgkmcnt(4)
	v_mfma_f32_16x16x32_bf16 v[88:91], v[250:253], v[38:41], v[88:91]
	ds_read_b128 v[250:253], v147 offset:21952
	s_waitcnt lgkmcnt(4)
	v_mfma_f32_16x16x32_bf16 v[92:95], v[172:175], v[38:41], v[92:95]
	ds_read_b128 v[172:175], v147 offset:26304
	s_waitcnt lgkmcnt(4)
	v_mfma_f32_16x16x32_bf16 v[168:171], v[198:201], v[38:41], v[168:171]
	ds_read_b128 v[198:201], v176 offset:17600
	s_waitcnt lgkmcnt(4)
	v_mfma_f32_16x16x32_bf16 v[84:87], v[202:205], v[38:41], v[84:87]
	v_lshl_add_u64 v[58:59], vcc, 0, v[76:77]
	s_waitcnt vmcnt(8) lgkmcnt(3)
	v_mfma_f32_16x16x32_bf16 v[42:45], v[246:249], v[34:37], v[88:91]
	s_waitcnt lgkmcnt(2)
	v_mfma_f32_16x16x32_bf16 v[46:49], v[250:253], v[34:37], v[92:95]
	s_waitcnt lgkmcnt(1)
	v_mfma_f32_16x16x32_bf16 v[50:53], v[172:175], v[34:37], v[168:171]
	s_waitcnt lgkmcnt(0)
	v_mfma_f32_16x16x32_bf16 v[38:41], v[198:201], v[34:37], v[84:87]
	v_lshlrev_b64 v[34:35], 8, v[58:59]
	v_lshl_add_u64 v[34:35], s[16:17], 0, v[34:35]
	v_lshl_add_u64 v[34:35], v[34:35], 0, v[0:1]
	s_mov_b64 s[16:17], 0x10000000
	v_lshl_add_u64 v[36:37], v[34:35], 0, s[16:17]
	v_add_co_u32_e32 v34, vcc, s15, v34
	v_lshlrev_b64 v[58:59], 11, v[58:59]
	s_nop 0
	v_addc_co_u32_e32 v35, vcc, 0, v35, vcc
	global_load_dwordx4 v[54:57], v[34:35], off
	s_nop 0
	global_load_dwordx4 v[34:37], v[36:37], off offset:16
	s_barrier
	ds_write2_b32 v166, v42, v43 offset1:132
	v_add_u32_e32 v42, 0x400, v166
	ds_write2_b32 v42, v44, v45 offset0:8 offset1:140
	v_add_u32_e32 v42, 0x2000, v166
	ds_write2_b32 v42, v46, v47 offset0:64 offset1:196
	v_add_u32_e32 v42, 0x2400, v166
	ds_write2_b32 v42, v48, v49 offset0:72 offset1:204
	v_add_u32_e32 v42, 0x4200, v166
	ds_write2_b32 v42, v50, v51 offset1:132
	v_add_u32_e32 v42, 0x4600, v166
	ds_write2_b32 v42, v52, v53 offset0:8 offset1:140
	v_add_u32_e32 v42, 0x6200, v166
	ds_write2_b32 v42, v38, v39 offset0:64 offset1:196
	v_add_u32_e32 v38, 0x6600, v166
	ds_write2_b32 v38, v40, v41 offset0:72 offset1:204
	s_waitcnt lgkmcnt(0)
	s_barrier
	ds_read_b128 v[50:53], v162
	ds_read_b128 v[46:49], v162 offset:16
	ds_read_b128 v[42:45], v162 offset:32
	ds_read_b128 v[38:41], v162 offset:48
	v_lshl_add_u64 v[58:59], s[74:75], 0, v[58:59]
	s_waitcnt lgkmcnt(3)
	v_pk_mul_f32 v[60:61], v[52:53], v[52:53]
	v_pk_mul_f32 v[62:63], v[50:51], v[50:51]
	v_lshl_add_u64 v[58:59], v[58:59], 0, s[80:81]
	v_pk_mov_b32 v[64:65], v[62:63], v[60:61] op_sel:[1,0]
	v_mov_b32_e32 v63, v61
	v_pk_add_f32 v[60:61], v[64:65], v[62:63]
	s_waitcnt lgkmcnt(2)
	v_pk_mul_f32 v[62:63], v[48:49], v[48:49]
	v_pk_mul_f32 v[64:65], v[46:47], v[46:47]
	v_pk_add_f32 v[60:61], v[60:61], v[60:61] op_sel:[0,1] op_sel_hi:[1,0]
	v_pk_mov_b32 v[84:85], v[64:65], v[62:63] op_sel:[1,0]
	v_mov_b32_e32 v65, v63
	v_pk_add_f32 v[62:63], v[84:85], v[64:65]
	s_waitcnt lgkmcnt(0)
	v_mul_f32_e32 v64, v38, v38
	v_mul_f32_e32 v65, v39, v39
	v_pk_add_f32 v[62:63], v[62:63], v[62:63] op_sel:[0,1] op_sel_hi:[1,0]
	v_mov_b32_e32 v61, v64
	v_mov_b32_e32 v63, v65
	v_pk_add_f32 v[60:61], v[60:61], v[62:63]
	v_mul_f32_e32 v62, v43, v43
	v_mul_f32_e32 v64, v45, v45
	v_mul_f32_e32 v84, v40, v40
	v_mul_f32_e32 v85, v41, v41
	v_pk_fma_f32 v[62:63], v[42:43], v[42:43], v[62:63] op_sel_hi:[1,1,0]
	v_pk_fma_f32 v[64:65], v[44:45], v[44:45], v[64:65] op_sel_hi:[1,1,0]
	v_mov_b32_e32 v63, v84
	v_mov_b32_e32 v65, v85
	v_pk_add_f32 v[62:63], v[62:63], v[64:65]
	v_lshl_add_u64 v[86:87], v[58:59], 0, v[0:1]
	v_pk_add_f32 v[60:61], v[60:61], v[62:63]
	s_waitcnt vmcnt(1)
	v_lshlrev_b32_e32 v92, 16, v54
	v_add_f32_e32 v60, v60, v61
	ds_bpermute_b32 v61, v97, v60
	v_and_b32_e32 v93, 0xffff0000, v54
	v_lshlrev_b32_e32 v94, 16, v55
	v_and_b32_e32 v95, 0xffff0000, v55
	v_lshlrev_b32_e32 v88, 16, v56
	s_waitcnt lgkmcnt(0)
	v_add_f32_e32 v60, v60, v61
	ds_bpermute_b32 v61, v98, v60
	v_and_b32_e32 v89, 0xffff0000, v56
	v_lshlrev_b32_e32 v90, 16, v57
	v_and_b32_e32 v91, 0xffff0000, v57
	s_waitcnt lgkmcnt(0)
	v_add_f32_e32 v60, v60, v61
	ds_bpermute_b32 v61, v163, v60
	s_waitcnt lgkmcnt(0)
	v_add_f32_e32 v60, v60, v61
	v_fmamk_f32 v60, v60, 0x3c000000, v178
	v_cmp_gt_f32_e32 vcc, s22, v60
	v_mul_f32_e32 v61, 0x4b800000, v60
	s_nop 0
	v_cndmask_b32_e32 v60, v60, v61, vcc
	v_rsq_f32_e32 v60, v60
	s_nop 0
	v_mul_f32_e32 v61, 0x45800000, v60
	v_cndmask_b32_e32 v84, v60, v61, vcc
	v_pk_mul_f32 v[52:53], v[52:53], v[84:85] op_sel_hi:[1,0]
	v_pk_mul_f32 v[50:51], v[50:51], v[84:85] op_sel_hi:[1,0]
	v_pk_mul_f32 v[48:49], v[48:49], v[84:85] op_sel_hi:[1,0]
	v_pk_mul_f32 v[46:47], v[46:47], v[84:85] op_sel_hi:[1,0]
	v_pk_mul_f32 v[44:45], v[44:45], v[84:85] op_sel_hi:[1,0]
	v_pk_mul_f32 v[42:43], v[42:43], v[84:85] op_sel_hi:[1,0]
	v_pk_mul_f32 v[40:41], v[40:41], v[84:85] op_sel_hi:[1,0]
	v_pk_mul_f32 v[38:39], v[38:39], v[84:85] op_sel_hi:[1,0]
	s_and_b64 vcc, exec, s[12:13]
	v_pk_mul_f32 v[38:39], v[232:233], v[38:39]
	v_pk_mul_f32 v[42:43], v[228:229], v[42:43]
	v_pk_mul_f32 v[46:47], v[224:225], v[46:47]
	v_pk_mul_f32 v[50:51], v[220:221], v[50:51]
	v_pk_mul_f32 v[52:53], v[222:223], v[52:53]
	v_pk_mul_f32 v[48:49], v[226:227], v[48:49]
	v_pk_mul_f32 v[52:53], v[52:53], v[94:95]
	v_pk_mul_f32 v[50:51], v[50:51], v[92:93]
	v_pk_mul_f32 v[62:63], v[48:49], v[90:91]
	v_pk_mul_f32 v[48:49], v[46:47], v[88:89]
	v_cvt_pk_bf16_f32 v46, v50, v51
	v_cvt_pk_bf16_f32 v47, v52, v53
	v_cvt_pk_bf16_f32 v48, v48, v49
	v_cvt_pk_bf16_f32 v49, v62, v63
	global_store_dwordx4 v[86:87], v[46:49], off offset:1024
	v_pk_mul_f32 v[44:45], v[230:231], v[44:45]
	v_pk_mul_f32 v[40:41], v[234:235], v[40:41]
	s_waitcnt vmcnt(1)
	v_lshlrev_b32_e32 v46, 16, v34
	v_and_b32_e32 v47, 0xffff0000, v34
	v_lshlrev_b32_e32 v34, 16, v35
	v_and_b32_e32 v35, 0xffff0000, v35
	v_lshlrev_b32_e32 v48, 16, v36
	v_and_b32_e32 v49, 0xffff0000, v36
	v_lshlrev_b32_e32 v36, 16, v37
	v_and_b32_e32 v37, 0xffff0000, v37
	v_pk_mul_f32 v[44:45], v[44:45], v[34:35]
	v_pk_mul_f32 v[34:35], v[42:43], v[46:47]
	v_pk_mul_f32 v[40:41], v[40:41], v[36:37]
	v_pk_mul_f32 v[36:37], v[38:39], v[48:49]
	v_cvt_pk_bf16_f32 v34, v34, v35
	v_cvt_pk_bf16_f32 v35, v44, v45
	v_cvt_pk_bf16_f32 v36, v36, v37
	v_cvt_pk_bf16_f32 v37, v40, v41
	global_store_dwordx4 v[86:87], v[34:37], off offset:1040
	s_barrier
	s_cbranch_vccnz .LBB0_455

.LBB0_744:
	ds_read_b128 v[80:83], v226
	ds_read_b128 v[84:87], v226 offset:1024
	ds_read_b128 v[88:91], v226 offset:2048
	ds_read_b128 v[92:95], v226 offset:3072
	ds_read_b128 v[128:131], v227
	ds_read_b128 v[132:135], v227 offset:1024
	ds_read_b128 v[152:155], v227 offset:2048
	ds_read_b128 v[156:159], v227 offset:3072
	s_add_u32 s26, s46, 0xfffc0080
	s_addc_u32 s27, s47, -1
	s_cmp_eq_u32 s25, 12
	s_cselect_b32 s89, s11, s27
	s_cselect_b32 s88, s14, s26
	s_cselect_b32 s49, s15, s24
	s_cselect_b32 s48, s16, s17
	v_lshl_add_u64 v[208:209], s[46:47], 0, v[184:185]
	s_add_i32 m0, s13, 0xc000
	ds_read_b128 v[160:163], v228
	ds_read_b128 v[164:167], v228 offset:1024
	ds_read_b128 v[168:171], v228 offset:2048
	ds_read_b128 v[172:175], v228 offset:3072
	ds_read_b128 v[192:195], v228 offset:4096
	ds_read_b128 v[196:199], v228 offset:5120
	ds_read_b128 v[200:203], v228 offset:6144
	ds_read_b128 v[204:207], v228 offset:7168
	global_load_lds_dwordx4 v[208:209], off
	v_lshl_add_u64 v[208:209], s[46:47], 0, v[186:187]
	s_add_i32 m0, s13, 0xe000
	s_nop 0
	global_load_lds_dwordx4 v[208:209], off
	s_waitcnt vmcnt(8)
	s_waitcnt lgkmcnt(0)
	s_barrier
	s_setprio 1
	s_waitcnt lgkmcnt(0)
	v_mfma_f32_16x16x32_bf16 v[76:79], v[80:83], v[160:163], v[76:79]
	v_mfma_f32_16x16x32_bf16 v[64:67], v[88:91], v[160:163], v[64:67]
	v_mfma_f32_16x16x32_bf16 v[148:151], v[80:83], v[168:171], v[148:151]
	v_mfma_f32_16x16x32_bf16 v[140:143], v[88:91], v[168:171], v[140:143]
	v_mfma_f32_16x16x32_bf16 v[124:127], v[80:83], v[192:195], v[124:127]
	v_mfma_f32_16x16x32_bf16 v[120:123], v[88:91], v[192:195], v[120:123]
	v_mfma_f32_16x16x32_bf16 v[72:75], v[80:83], v[200:203], v[72:75]
	v_mfma_f32_16x16x32_bf16 v[60:63], v[88:91], v[200:203], v[60:63]
	v_mfma_f32_16x16x32_bf16 v[76:79], v[84:87], v[164:167], v[76:79]
	v_mfma_f32_16x16x32_bf16 v[64:67], v[92:95], v[164:167], v[64:67]
	v_mfma_f32_16x16x32_bf16 v[148:151], v[84:87], v[172:175], v[148:151]
	v_mfma_f32_16x16x32_bf16 v[140:143], v[92:95], v[172:175], v[140:143]
	v_mfma_f32_16x16x32_bf16 v[124:127], v[84:87], v[196:199], v[124:127]
	v_mfma_f32_16x16x32_bf16 v[120:123], v[92:95], v[196:199], v[120:123]
	v_mfma_f32_16x16x32_bf16 v[72:75], v[84:87], v[204:207], v[72:75]
	v_mfma_f32_16x16x32_bf16 v[60:63], v[92:95], v[204:207], v[60:63]
	s_setprio 0
	s_setprio 1
	v_mfma_f32_16x16x32_bf16 v[144:147], v[128:131], v[160:163], v[144:147]
	v_mfma_f32_16x16x32_bf16 v[136:139], v[152:155], v[160:163], v[136:139]
	v_mfma_f32_16x16x32_bf16 v[116:119], v[128:131], v[168:171], v[116:119]
	v_mfma_f32_16x16x32_bf16 v[112:115], v[152:155], v[168:171], v[112:115]
	v_mfma_f32_16x16x32_bf16 v[108:111], v[128:131], v[192:195], v[108:111]
	v_mfma_f32_16x16x32_bf16 v[104:107], v[152:155], v[192:195], v[104:107]
	v_mfma_f32_16x16x32_bf16 v[100:103], v[128:131], v[200:203], v[100:103]
	v_mfma_f32_16x16x32_bf16 v[96:99], v[152:155], v[200:203], v[96:99]
	v_mfma_f32_16x16x32_bf16 v[144:147], v[132:135], v[164:167], v[144:147]
	v_mfma_f32_16x16x32_bf16 v[136:139], v[156:159], v[164:167], v[136:139]
	v_mfma_f32_16x16x32_bf16 v[116:119], v[132:135], v[172:175], v[116:119]
	v_mfma_f32_16x16x32_bf16 v[112:115], v[156:159], v[172:175], v[112:115]
	v_mfma_f32_16x16x32_bf16 v[108:111], v[132:135], v[196:199], v[108:111]
	v_mfma_f32_16x16x32_bf16 v[104:107], v[156:159], v[196:199], v[104:107]
	v_mfma_f32_16x16x32_bf16 v[100:103], v[132:135], v[204:207], v[100:103]
	v_mfma_f32_16x16x32_bf16 v[96:99], v[156:159], v[204:207], v[96:99]
	s_setprio 0
	s_barrier
	s_add_i32 s26, s3, s20
	v_lshl_add_u64 v[208:209], s[48:49], 0, v[178:179]
	s_mov_b32 m0, s26
	ds_read_b128 v[160:163], v228 offset:16384
	ds_read_b128 v[164:167], v228 offset:17408
	ds_read_b128 v[168:171], v228 offset:18432
	ds_read_b128 v[172:175], v228 offset:19456
	ds_read_b128 v[192:195], v228 offset:20480
	ds_read_b128 v[196:199], v228 offset:21504
	ds_read_b128 v[200:203], v228 offset:22528
	ds_read_b128 v[204:207], v228 offset:23552
	global_load_lds_dwordx4 v[208:209], off
	s_add_i32 m0, s26, 0x2000
	s_add_u32 s26, s48, 0x40000
	v_lshl_add_u64 v[210:211], s[48:49], 0, v[182:183]
	s_addc_u32 s27, s49, 0
	s_add_i32 s28, s93, s20
	global_load_lds_dwordx4 v[210:211], off
	v_lshl_add_u64 v[212:213], s[26:27], 0, v[178:179]
	s_mov_b32 m0, s28
	v_lshl_add_u64 v[230:231], s[88:89], 0, v[180:181]
	global_load_lds_dwordx4 v[212:213], off
	v_lshl_add_u64 v[212:213], s[26:27], 0, v[182:183]
	s_add_i32 m0, s28, 0x2000
	s_nop 0
	global_load_lds_dwordx4 v[212:213], off
	v_lshl_add_u64 v[212:213], s[88:89], 0, v[176:177]
	s_mov_b32 m0, s13
	s_nop 0
	global_load_lds_dwordx4 v[212:213], off
	s_mov_b32 m0, s21
	s_nop 0
	global_load_lds_dwordx4 v[230:231], off
	s_waitcnt vmcnt(8)
	s_waitcnt lgkmcnt(0)
	s_barrier
	s_setprio 1
	s_waitcnt lgkmcnt(0)
	v_mfma_f32_16x16x32_bf16 v[68:71], v[80:83], v[160:163], v[68:71]
	v_mfma_f32_16x16x32_bf16 v[36:39], v[88:91], v[160:163], v[36:39]
	v_mfma_f32_16x16x32_bf16 v[52:55], v[80:83], v[168:171], v[52:55]
	v_mfma_f32_16x16x32_bf16 v[44:47], v[88:91], v[168:171], v[44:47]
	v_mfma_f32_16x16x32_bf16 v[28:31], v[80:83], v[192:195], v[28:31]
	v_mfma_f32_16x16x32_bf16 v[24:27], v[88:91], v[192:195], v[24:27]
	v_mfma_f32_16x16x32_bf16 v[56:59], v[80:83], v[200:203], v[56:59]
	v_mfma_f32_16x16x32_bf16 v[32:35], v[88:91], v[200:203], v[32:35]
	v_mfma_f32_16x16x32_bf16 v[68:71], v[84:87], v[164:167], v[68:71]
	v_mfma_f32_16x16x32_bf16 v[36:39], v[92:95], v[164:167], v[36:39]
	v_mfma_f32_16x16x32_bf16 v[52:55], v[84:87], v[172:175], v[52:55]
	v_mfma_f32_16x16x32_bf16 v[44:47], v[92:95], v[172:175], v[44:47]
	v_mfma_f32_16x16x32_bf16 v[28:31], v[84:87], v[196:199], v[28:31]
	v_mfma_f32_16x16x32_bf16 v[24:27], v[92:95], v[196:199], v[24:27]
	v_mfma_f32_16x16x32_bf16 v[56:59], v[84:87], v[204:207], v[56:59]
	v_mfma_f32_16x16x32_bf16 v[32:35], v[92:95], v[204:207], v[32:35]
	s_setprio 0
	s_setprio 1
	v_mfma_f32_16x16x32_bf16 v[48:51], v[128:131], v[160:163], v[48:51]
	v_mfma_f32_16x16x32_bf16 v[40:43], v[152:155], v[160:163], v[40:43]
	v_mfma_f32_16x16x32_bf16 v[20:23], v[128:131], v[168:171], v[20:23]
	v_mfma_f32_16x16x32_bf16 v[16:19], v[152:155], v[168:171], v[16:19]
	v_mfma_f32_16x16x32_bf16 v[12:15], v[128:131], v[192:195], v[12:15]
	v_mfma_f32_16x16x32_bf16 v[8:11], v[152:155], v[192:195], v[8:11]
	v_mfma_f32_16x16x32_bf16 v[4:7], v[128:131], v[200:203], v[4:7]
	v_mfma_f32_16x16x32_bf16 v[0:3], v[152:155], v[200:203], v[0:3]
	v_mfma_f32_16x16x32_bf16 v[48:51], v[132:135], v[164:167], v[48:51]
	v_mfma_f32_16x16x32_bf16 v[40:43], v[156:159], v[164:167], v[40:43]
	v_mfma_f32_16x16x32_bf16 v[20:23], v[132:135], v[172:175], v[20:23]
	v_mfma_f32_16x16x32_bf16 v[16:19], v[156:159], v[172:175], v[16:19]
	v_mfma_f32_16x16x32_bf16 v[12:15], v[132:135], v[196:199], v[12:15]
	v_mfma_f32_16x16x32_bf16 v[8:11], v[156:159], v[196:199], v[8:11]
	v_mfma_f32_16x16x32_bf16 v[4:7], v[132:135], v[204:207], v[4:7]
	v_mfma_f32_16x16x32_bf16 v[0:3], v[156:159], v[204:207], v[0:3]
	s_setprio 0
	s_barrier
	s_add_i32 s28, 0, 0x18000
	s_add_i32 s29, 0, 0x1c000
	v_add_u32_e32 v92, s28, v218
	v_add_u32_e32 v156, s29, v218
	ds_read_b128 v[80:83], v92
	ds_read_b128 v[84:87], v92 offset:1024
	ds_read_b128 v[88:91], v92 offset:2048
	ds_read_b128 v[92:95], v92 offset:3072
	ds_read_b128 v[128:131], v156
	ds_read_b128 v[132:135], v156 offset:1024
	ds_read_b128 v[152:155], v156 offset:2048
	ds_read_b128 v[156:159], v156 offset:3072
	s_add_u32 s26, s88, 0x40000
	s_addc_u32 s27, s89, 0
	s_mov_b32 m0, s22
	v_lshl_add_u64 v[232:233], s[26:27], 0, v[176:177]
	ds_read_b128 v[160:163], v228 offset:32768
	ds_read_b128 v[164:167], v228 offset:33792
	ds_read_b128 v[168:171], v228 offset:34816
	ds_read_b128 v[172:175], v228 offset:35840
	ds_read_b128 v[192:195], v228 offset:36864
	ds_read_b128 v[196:199], v228 offset:37888
	ds_read_b128 v[200:203], v228 offset:38912
	ds_read_b128 v[204:207], v228 offset:39936
	global_load_lds_dwordx4 v[232:233], off
	v_lshl_add_u64 v[232:233], s[26:27], 0, v[180:181]
	s_mov_b32 m0, s23
	s_nop 0
	global_load_lds_dwordx4 v[232:233], off
	s_waitcnt vmcnt(8)
	s_waitcnt lgkmcnt(0)
	s_barrier
	s_setprio 1
	s_waitcnt lgkmcnt(0)
	v_mfma_f32_16x16x32_bf16 v[76:79], v[80:83], v[160:163], v[76:79]
	v_mfma_f32_16x16x32_bf16 v[64:67], v[88:91], v[160:163], v[64:67]
	v_mfma_f32_16x16x32_bf16 v[148:151], v[80:83], v[168:171], v[148:151]
	v_mfma_f32_16x16x32_bf16 v[140:143], v[88:91], v[168:171], v[140:143]
	v_mfma_f32_16x16x32_bf16 v[124:127], v[80:83], v[192:195], v[124:127]
	v_mfma_f32_16x16x32_bf16 v[120:123], v[88:91], v[192:195], v[120:123]
	v_mfma_f32_16x16x32_bf16 v[72:75], v[80:83], v[200:203], v[72:75]
	v_mfma_f32_16x16x32_bf16 v[60:63], v[88:91], v[200:203], v[60:63]
	v_mfma_f32_16x16x32_bf16 v[76:79], v[84:87], v[164:167], v[76:79]
	v_mfma_f32_16x16x32_bf16 v[64:67], v[92:95], v[164:167], v[64:67]
	v_mfma_f32_16x16x32_bf16 v[148:151], v[84:87], v[172:175], v[148:151]
	v_mfma_f32_16x16x32_bf16 v[140:143], v[92:95], v[172:175], v[140:143]
	v_mfma_f32_16x16x32_bf16 v[124:127], v[84:87], v[196:199], v[124:127]
	v_mfma_f32_16x16x32_bf16 v[120:123], v[92:95], v[196:199], v[120:123]
	v_mfma_f32_16x16x32_bf16 v[72:75], v[84:87], v[204:207], v[72:75]
	v_mfma_f32_16x16x32_bf16 v[60:63], v[92:95], v[204:207], v[60:63]
	s_setprio 0
	s_setprio 1
	v_mfma_f32_16x16x32_bf16 v[144:147], v[128:131], v[160:163], v[144:147]
	v_mfma_f32_16x16x32_bf16 v[136:139], v[152:155], v[160:163], v[136:139]
	v_mfma_f32_16x16x32_bf16 v[116:119], v[128:131], v[168:171], v[116:119]
	v_mfma_f32_16x16x32_bf16 v[112:115], v[152:155], v[168:171], v[112:115]
	v_mfma_f32_16x16x32_bf16 v[108:111], v[128:131], v[192:195], v[108:111]
	v_mfma_f32_16x16x32_bf16 v[104:107], v[152:155], v[192:195], v[104:107]
	v_mfma_f32_16x16x32_bf16 v[100:103], v[128:131], v[200:203], v[100:103]
	v_mfma_f32_16x16x32_bf16 v[96:99], v[152:155], v[200:203], v[96:99]
	v_mfma_f32_16x16x32_bf16 v[144:147], v[132:135], v[164:167], v[144:147]
	v_mfma_f32_16x16x32_bf16 v[136:139], v[156:159], v[164:167], v[136:139]
	v_mfma_f32_16x16x32_bf16 v[116:119], v[132:135], v[172:175], v[116:119]
	v_mfma_f32_16x16x32_bf16 v[112:115], v[156:159], v[172:175], v[112:115]
	v_mfma_f32_16x16x32_bf16 v[108:111], v[132:135], v[196:199], v[108:111]
	v_mfma_f32_16x16x32_bf16 v[104:107], v[156:159], v[196:199], v[104:107]
	v_mfma_f32_16x16x32_bf16 v[100:103], v[132:135], v[204:207], v[100:103]
	v_mfma_f32_16x16x32_bf16 v[96:99], v[156:159], v[204:207], v[96:99]
	s_setprio 0
	s_barrier
	s_add_i32 s26, s28, s20
	v_lshl_add_u64 v[208:209], v[208:209], 0, s[6:7]
	s_mov_b32 m0, s26
	ds_read_b128 v[160:163], v228 offset:49152
	ds_read_b128 v[164:167], v228 offset:50176
	ds_read_b128 v[168:171], v228 offset:51200
	ds_read_b128 v[172:175], v228 offset:52224
	ds_read_b128 v[192:195], v228 offset:53248
	ds_read_b128 v[196:199], v228 offset:54272
	ds_read_b128 v[200:203], v228 offset:55296
	ds_read_b128 v[204:207], v228 offset:56320
	global_load_lds_dwordx4 v[208:209], off
	s_add_i32 m0, s26, 0x2000
	s_add_u32 s26, s48, 0x40080
	v_lshl_add_u64 v[208:209], v[210:211], 0, s[6:7]
	s_addc_u32 s27, s49, 0
	s_add_i32 s28, s29, s20
	global_load_lds_dwordx4 v[208:209], off
	v_lshl_add_u64 v[208:209], s[26:27], 0, v[178:179]
	s_mov_b32 m0, s28
	s_nop 0
	global_load_lds_dwordx4 v[208:209], off
	v_lshl_add_u64 v[208:209], s[26:27], 0, v[182:183]
	s_add_i32 m0, s28, 0x2000
	s_nop 0
	global_load_lds_dwordx4 v[208:209], off
	v_lshl_add_u64 v[208:209], v[212:213], 0, s[6:7]
	s_mov_b32 m0, s71
	s_nop 0
	global_load_lds_dwordx4 v[208:209], off
	v_lshl_add_u64 v[208:209], v[230:231], 0, s[6:7]
	s_mov_b32 m0, s73
	s_nop 0
	global_load_lds_dwordx4 v[208:209], off
	s_waitcnt vmcnt(8)
	s_waitcnt lgkmcnt(0)
	s_barrier
	s_setprio 1
	s_waitcnt lgkmcnt(0)
	v_mfma_f32_16x16x32_bf16 v[68:71], v[80:83], v[160:163], v[68:71]
	v_mfma_f32_16x16x32_bf16 v[36:39], v[88:91], v[160:163], v[36:39]
	v_mfma_f32_16x16x32_bf16 v[52:55], v[80:83], v[168:171], v[52:55]
	v_mfma_f32_16x16x32_bf16 v[44:47], v[88:91], v[168:171], v[44:47]
	v_mfma_f32_16x16x32_bf16 v[28:31], v[80:83], v[192:195], v[28:31]
	v_mfma_f32_16x16x32_bf16 v[24:27], v[88:91], v[192:195], v[24:27]
	v_mfma_f32_16x16x32_bf16 v[56:59], v[80:83], v[200:203], v[56:59]
	v_mfma_f32_16x16x32_bf16 v[32:35], v[88:91], v[200:203], v[32:35]
	v_mfma_f32_16x16x32_bf16 v[68:71], v[84:87], v[164:167], v[68:71]
	v_mfma_f32_16x16x32_bf16 v[36:39], v[92:95], v[164:167], v[36:39]
	v_mfma_f32_16x16x32_bf16 v[52:55], v[84:87], v[172:175], v[52:55]
	v_mfma_f32_16x16x32_bf16 v[44:47], v[92:95], v[172:175], v[44:47]
	v_mfma_f32_16x16x32_bf16 v[28:31], v[84:87], v[196:199], v[28:31]
	v_mfma_f32_16x16x32_bf16 v[24:27], v[92:95], v[196:199], v[24:27]
	v_mfma_f32_16x16x32_bf16 v[56:59], v[84:87], v[204:207], v[56:59]
	v_mfma_f32_16x16x32_bf16 v[32:35], v[92:95], v[204:207], v[32:35]
	s_setprio 0
	s_setprio 1
	v_mfma_f32_16x16x32_bf16 v[48:51], v[128:131], v[160:163], v[48:51]
	v_mfma_f32_16x16x32_bf16 v[40:43], v[152:155], v[160:163], v[40:43]
	v_mfma_f32_16x16x32_bf16 v[20:23], v[128:131], v[168:171], v[20:23]
	v_mfma_f32_16x16x32_bf16 v[16:19], v[152:155], v[168:171], v[16:19]
	v_mfma_f32_16x16x32_bf16 v[12:15], v[128:131], v[192:195], v[12:15]
	v_mfma_f32_16x16x32_bf16 v[8:11], v[152:155], v[192:195], v[8:11]
	v_mfma_f32_16x16x32_bf16 v[4:7], v[128:131], v[200:203], v[4:7]
	v_mfma_f32_16x16x32_bf16 v[0:3], v[152:155], v[200:203], v[0:3]
	v_mfma_f32_16x16x32_bf16 v[48:51], v[132:135], v[164:167], v[48:51]
	v_mfma_f32_16x16x32_bf16 v[40:43], v[156:159], v[164:167], v[40:43]
	v_mfma_f32_16x16x32_bf16 v[20:23], v[132:135], v[172:175], v[20:23]
	v_mfma_f32_16x16x32_bf16 v[16:19], v[156:159], v[172:175], v[16:19]
	v_mfma_f32_16x16x32_bf16 v[12:15], v[132:135], v[196:199], v[12:15]
	v_mfma_f32_16x16x32_bf16 v[8:11], v[156:159], v[196:199], v[8:11]
	v_mfma_f32_16x16x32_bf16 v[4:7], v[132:135], v[204:207], v[4:7]
	v_mfma_f32_16x16x32_bf16 v[0:3], v[156:159], v[204:207], v[0:3]
	s_setprio 0
	s_barrier
	s_add_i32 s25, s25, 2
	s_add_u32 s46, s46, 0x100
	s_addc_u32 s47, s47, 0
	s_add_u32 s17, s17, 0x100
	s_addc_u32 s24, s24, 0
	s_cmp_gt_u32 s25, 13
	s_cbranch_scc0 .LBB0_744
	v_mov_b32_e32 v80, v214
	s_movk_i32 s14, 0x100
	s_lshl_b32 s11, s10, 8
	s_nop 0
	v_cmp_gt_i32_e32 vcc, s14, v80
	s_and_saveexec_b64 s[46:47], vcc
	s_cbranch_execz .Lp8_noss
	v_add_u32_e32 v82, s11, v80
	v_ashrrev_i32_e32 v83, 31, v82
	v_lshlrev_b64 v[82:83], 6, v[82:83]
	v_lshl_add_u64 v[94:95], s[0:1], 0, v[82:83]
	global_load_dwordx4 v[82:85], v[94:95], off
	global_load_dwordx4 v[86:89], v[94:95], off offset:16
	global_load_dwordx4 v[90:93], v[94:95], off offset:32
	global_load_dwordx4 v[128:131], v[94:95], off offset:48
.Lp8_noss:
	s_or_b64 exec, exec, s[46:47]
	s_and_b64 vcc, exec, s[8:9]
	s_cbranch_vccz .LBB0_747
	s_barrier
.LBB0_747:
	v_cmp_gt_i32_e32 vcc, s14, v80
	s_and_saveexec_b64 s[46:47], vcc
	s_cbranch_execz .LBB0_749
	s_mov_b32 s14, 0x800000
	v_lshl_add_u32 v80, v80, 2, 0
	v_add_u32_e32 v80, 0x21000, v80
	s_waitcnt vmcnt(0)
	v_pk_add_f32 v[84:85], v[84:85], v[88:89]
	v_pk_add_f32 v[82:83], v[82:83], v[86:87]
	v_pk_add_f32 v[86:87], v[92:93], v[130:131]
	v_pk_add_f32 v[88:89], v[90:91], v[128:129]
	v_pk_add_f32 v[84:85], v[84:85], v[86:87]
	v_pk_add_f32 v[82:83], v[82:83], v[88:89]
	s_nop 0
	v_pk_mov_b32 v[86:87], v[82:83], v[84:85] op_sel:[1,0]
	v_mov_b32_e32 v83, v85
	v_pk_add_f32 v[82:83], v[86:87], v[82:83]
	s_nop 0
	v_add_f32_e32 v81, v82, v83
	v_fmamk_f32 v81, v81, 0x3a800000, v229
	v_mul_f32_e32 v82, 0x4b800000, v81
	v_cmp_gt_f32_e32 vcc, s14, v81
	s_nop 1
	v_cndmask_b32_e32 v81, v81, v82, vcc
	v_rsq_f32_e32 v81, v81
	s_nop 0
	v_mul_f32_e32 v82, 0x45800000, v81
	v_cndmask_b32_e32 v81, v81, v82, vcc
	ds_write_b32 v80, v81
